# prologue cooperative-groups grid sync also replaced by the hand-written XCD slot barrier (with vmcnt(0) before the arrival)
# speedup vs baseline: 1.0098x; 1.0050x over previous
.LBB0_148:
	v_lshrrev_b32_e32 v1, 20, v0
	v_lshrrev_b32_e32 v0, 10, v0
	v_or_b32_e32 v0, v0, v1
	s_movk_i32 s3, 0x3ff
	v_and_or_b32 v0, v0, s3, v237
	v_cmp_eq_u32_e32 vcc, 0, v0
	s_waitcnt vmcnt(0) lgkmcnt(0)
	s_barrier
	s_and_saveexec_b64 s[4:5], vcc
	s_cbranch_execz .LBB0_158
	s_getreg_b32 s6, hwreg(HW_REG_XCC_ID, 0, 4)
	s_mov_b32 s7, 0x21000
	s_mov_b32 s8, 0x21004
	s_and_b32 s6, s6, 15
	s_lshl_b32 s6, s6, 8
	v_mov_b32_e32 v0, s7
	v_mov_b32_e32 v2, s8
	ds_read_b32 v3, v0
	ds_read_b32 v2, v2
	s_add_i32 s9, s6, 0x1400
	s_add_i32 s10, s6, 0x4000
	s_waitcnt vmcnt(0) lgkmcnt(0)
	v_cmp_ne_u32_e32 vcc, 0, v3
	s_cbranch_vccnz .Lmy_xb4_have
	s_mov_b32 s12, 0
.Lmy_xb4_disc:
	v_mov_b32_e32 v0, 0x400
	global_load_dword v2, v0, s[36:37] sc1
	global_load_dword v3, v0, s[36:37] offset:256 sc1
	global_load_dword v4, v0, s[36:37] offset:512 sc1
	global_load_dword v5, v0, s[36:37] offset:768 sc1
	global_load_dword v6, v0, s[36:37] offset:1024 sc1
	global_load_dword v7, v0, s[36:37] offset:1280 sc1
	global_load_dword v8, v0, s[36:37] offset:1536 sc1
	global_load_dword v9, v0, s[36:37] offset:1792 sc1
	global_load_dword v10, v0, s[36:37] offset:2048 sc1
	global_load_dword v11, v0, s[36:37] offset:2304 sc1
	global_load_dword v12, v0, s[36:37] offset:2560 sc1
	global_load_dword v13, v0, s[36:37] offset:2816 sc1
	global_load_dword v14, v0, s[36:37] offset:3072 sc1
	global_load_dword v15, v0, s[36:37] offset:3328 sc1
	global_load_dword v16, v0, s[36:37] offset:3584 sc1
	global_load_dword v17, v0, s[36:37] offset:3840 sc1
	s_mov_b32 s7, 0
	s_mov_b32 s8, 0
	s_waitcnt vmcnt(0)
	v_readfirstlane_b32 s13, v2
	s_add_i32 s7, s7, s13
	s_cmp_lg_u32 s13, 0
	s_addc_u32 s8, s8, 0
	v_readfirstlane_b32 s13, v3
	s_add_i32 s7, s7, s13
	s_cmp_lg_u32 s13, 0
	s_addc_u32 s8, s8, 0
	v_readfirstlane_b32 s13, v4
	s_add_i32 s7, s7, s13
	s_cmp_lg_u32 s13, 0
	s_addc_u32 s8, s8, 0
	v_readfirstlane_b32 s13, v5
	s_add_i32 s7, s7, s13
	s_cmp_lg_u32 s13, 0
	s_addc_u32 s8, s8, 0
	v_readfirstlane_b32 s13, v6
	s_add_i32 s7, s7, s13
	s_cmp_lg_u32 s13, 0
	s_addc_u32 s8, s8, 0
	v_readfirstlane_b32 s13, v7
	s_add_i32 s7, s7, s13
	s_cmp_lg_u32 s13, 0
	s_addc_u32 s8, s8, 0
	v_readfirstlane_b32 s13, v8
	s_add_i32 s7, s7, s13
	s_cmp_lg_u32 s13, 0
	s_addc_u32 s8, s8, 0
	v_readfirstlane_b32 s13, v9
	s_add_i32 s7, s7, s13
	s_cmp_lg_u32 s13, 0
	s_addc_u32 s8, s8, 0
	v_readfirstlane_b32 s13, v10
	s_add_i32 s7, s7, s13
	s_cmp_lg_u32 s13, 0
	s_addc_u32 s8, s8, 0
	v_readfirstlane_b32 s13, v11
	s_add_i32 s7, s7, s13
	s_cmp_lg_u32 s13, 0
	s_addc_u32 s8, s8, 0
	v_readfirstlane_b32 s13, v12
	s_add_i32 s7, s7, s13
	s_cmp_lg_u32 s13, 0
	s_addc_u32 s8, s8, 0
	v_readfirstlane_b32 s13, v13
	s_add_i32 s7, s7, s13
	s_cmp_lg_u32 s13, 0
	s_addc_u32 s8, s8, 0
	v_readfirstlane_b32 s13, v14
	s_add_i32 s7, s7, s13
	s_cmp_lg_u32 s13, 0
	s_addc_u32 s8, s8, 0
	v_readfirstlane_b32 s13, v15
	s_add_i32 s7, s7, s13
	s_cmp_lg_u32 s13, 0
	s_addc_u32 s8, s8, 0
	v_readfirstlane_b32 s13, v16
	s_add_i32 s7, s7, s13
	s_cmp_lg_u32 s13, 0
	s_addc_u32 s8, s8, 0
	v_readfirstlane_b32 s13, v17
	s_add_i32 s7, s7, s13
	s_cmp_lg_u32 s13, 0
	s_addc_u32 s8, s8, 0
	s_cmp_eq_u32 s7, s34
	s_cbranch_scc1 .Lmy_xb4_disc_ok
	s_sleep 1
	s_add_i32 s12, s12, 1
	s_cmp_lt_u32 s12, 0x40000
	s_cbranch_scc1 .Lmy_xb4_disc
.Lmy_xb4_disc_ok:
	s_add_i32 s13, s6, 0x400
	v_mov_b32_e32 v0, s13
	global_load_dword v3, v0, s[36:37] sc1
	s_max_u32 s8, s8, 1
	v_mov_b32_e32 v2, s8
	s_mov_b32 s7, 0x21000
	s_mov_b32 s13, 0x21004
	v_mov_b32_e32 v4, s7
	v_mov_b32_e32 v5, s13
	s_waitcnt vmcnt(0)
	v_max_u32_e32 v3, 1, v3
	ds_write_b32 v4, v3
	ds_write_b32 v5, v2

.Lmy_xb4_acq:
	buffer_inv sc1
	s_waitcnt vmcnt(0)
.LBB0_158:
	s_or_b64 exec, exec, s[4:5]
	s_cmp_eq_u64 s[24:25], 0
	s_cselect_b64 s[92:93], -1, 0
	s_add_u32 s4, s36, 0x1a00000
	s_addc_u32 s5, s37, 0
	v_writelane_b32 v254, s4, 1
	s_lshl_b32 s94, s34, 11
	s_add_u32 s3, s36, 0x1c00000
	v_writelane_b32 v254, s5, 2
	v_writelane_b32 v254, s3, 3
	s_addc_u32 s3, s37, 0
	s_cmpk_lt_i32 s2, 0xb00
	s_cselect_b64 s[4:5], -1, 0
	s_ashr_i32 s83, s2, 31
	v_writelane_b32 v254, s3, 4
	s_lshr_b32 s3, s83, 29
	s_add_i32 s3, s2, s3
	s_ashr_i32 s9, s3, 3
	s_and_b32 s3, s3, -8
	s_sub_i32 s6, s2, s3
	v_writelane_b32 v254, s4, 5
	s_cmp_gt_i32 s6, -1
	s_mul_i32 s35, s35, s34
	v_writelane_b32 v254, s5, 6
	s_cselect_b64 s[4:5], -1, 0
	s_ashr_i32 s84, s34, 31
	s_add_u32 s60, s36, 0x7200000
	v_writelane_b32 v254, s4, 7
	s_addc_u32 s61, s37, 0
	v_mov_b32_e32 v238, 0x358637bd
	v_writelane_b32 v254, s5, 8
	s_add_u32 s4, s36, 0x12c00000
	s_addc_u32 s5, s37, 0
	v_writelane_b32 v254, s4, 9
	v_mov_b32_e32 v239, 1
	v_mbcnt_hi_u32_b32 v242, -1, v26
	v_writelane_b32 v254, s5, 10
	s_add_u32 s4, s36, 0x12600000
	s_addc_u32 s5, s37, 0
	v_writelane_b32 v254, s4, 11
	v_mov_b32_e32 v243, 0xff800000
	v_mov_b64_e32 v[184:185], 0x1ff
	v_writelane_b32 v254, s5, 12
	s_add_u32 s4, s36, 0x12900000
	s_addc_u32 s5, s37, 0
	s_add_u32 s98, s36, 0x200
	s_addc_u32 s99, s37, 0
	s_add_u32 s62, s36, 0x1000
	s_addc_u32 s63, s37, 0
	s_add_u32 s66, s36, 0x1100
	s_addc_u32 s67, s37, 0
	s_add_u32 s70, s36, 0x1200
	s_addc_u32 s71, s37, 0
	s_add_u32 s78, s36, 0x1300
	v_writelane_b32 v254, s4, 13
	s_addc_u32 s79, s37, 0
	v_mov_b64_e32 v[186:187], 0x200
	v_writelane_b32 v254, s5, 14
	s_add_u32 s4, s36, 0x3400
	s_addc_u32 s5, s37, 0
	s_add_u32 s80, s36, 0x3500
	s_addc_u32 s81, s37, 0
	s_lshl_b32 s3, s2, 4
	v_writelane_b32 v254, s4, 15
	s_and_b32 s3, s3, 0x70
	s_movk_i32 s85, 0x1800
	v_writelane_b32 v254, s5, 16
	s_add_u32 s4, s36, 0x100000
	v_writelane_b32 v254, s3, 17
	s_addc_u32 s5, s37, 0
	v_writelane_b32 v254, s4, 18
	s_mov_b32 s82, 0x3e38aa3b
	s_mov_b64 s[40:41], 0
	v_writelane_b32 v254, s5, 19
	s_add_u32 s4, s36, 0x400000
	s_addc_u32 s5, s37, 0
	s_add_u32 s10, s36, 0x13200000
	s_addc_u32 s11, s37, 0
	v_writelane_b32 v254, s4, 20
	s_cmpk_lt_i32 s2, 0x100
	s_mov_b32 s43, 0
	v_writelane_b32 v254, s5, 21
	s_cselect_b64 s[4:5], -1, 0
	s_lshl_b32 s12, s2, 7
	v_writelane_b32 v254, s4, 22
	s_ashr_i32 s13, s12, 31
	s_mov_b64 s[38:39], 0x80
	v_writelane_b32 v254, s5, 23
	s_lshl_b64 s[4:5], s[12:13], 1
	s_add_u32 s4, s10, s4
	v_writelane_b32 v254, s10, 24
	s_addc_u32 s5, s11, s5
	s_add_i32 s3, s33, -7
	v_writelane_b32 v254, s11, 25
	v_writelane_b32 v254, s4, 26
	s_add_u32 s7, s36, 0xc200000
	s_addc_u32 s8, s37, 0
	v_writelane_b32 v254, s5, 27
	v_writelane_b32 v254, s3, 28
	v_writelane_b32 v254, s7, 29
	s_add_u32 s4, s36, 0xd200000
	v_writelane_b32 v254, s8, 30
	s_addc_u32 s5, s37, 0
	v_writelane_b32 v254, s4, 31
	s_cmpk_lt_i32 s2, 0x400
	s_mov_b32 s96, 0x3dd2d3e7
	v_writelane_b32 v254, s5, 32
	s_cselect_b64 s[4:5], -1, 0
	v_writelane_b32 v254, s4, 33
	s_lshl_b32 s3, s2, 5
	s_and_b32 s10, s3, 0xfffff000
	v_writelane_b32 v254, s5, 34
	v_writelane_b32 v254, s3, 35
	v_writelane_b32 v254, s12, 36
	s_and_b32 s3, s12, 0xf80
	s_mov_b32 s4, s10
	v_writelane_b32 v254, s13, 37
	v_writelane_b32 v254, s3, 38
	s_addk_i32 s3, 0xff80
	v_writelane_b32 v254, s3, 39
	s_lshl_b32 s3, s2, 1
	s_and_b32 s12, s3, 0xc0
	s_or_b32 s3, s10, 64
	v_writelane_b32 v254, s3, 40
	s_or_b32 s3, s10, 0xc0
	v_writelane_b32 v254, s3, 41
	s_ashr_i32 s11, s10, 31
	v_writelane_b32 v254, s4, 42
	s_mov_b32 s88, 0xc0135761
	s_nop 0
	v_writelane_b32 v254, s5, 43
	s_lshl_b64 s[4:5], s[10:11], 1
	s_add_u32 s4, s7, s4
	s_addc_u32 s5, s8, s5
	v_writelane_b32 v254, s4, 44
	s_nop 1
	v_writelane_b32 v254, s5, 45
	s_add_u32 s4, s36, 0x2700000
	s_addc_u32 s5, s37, 0
	v_writelane_b32 v254, s4, 46
	s_cmpk_lt_i32 s2, 0x200
	s_nop 0
	v_writelane_b32 v254, s5, 47
	s_cselect_b64 s[4:5], -1, 0
	v_writelane_b32 v254, s4, 48
	s_cmpk_gt_i32 s2, 0x1ff
	s_nop 0
	v_writelane_b32 v254, s5, 49
	s_cselect_b64 s[4:5], -1, 0
	s_lshl_b32 s3, s6, 6
	s_add_u32 s52, s36, 0x1a80000
	v_writelane_b32 v254, s4, 50
	s_addc_u32 s53, s37, 0
	s_cmp_lt_i32 s6, 0
	v_writelane_b32 v254, s5, 51
	s_movk_i32 s5, 0x161
	s_cselect_b32 s5, s5, 0x160
	s_mul_i32 s4, s6, 0x41
	s_mul_i32 s5, s6, s5
	s_cselect_b32 s3, s4, s3
	s_add_i32 s5, s5, s9
	s_mul_hi_i32 s4, s5, 0x2e8ba2e9
	v_writelane_b32 v254, s6, 52
	s_lshr_b32 s6, s4, 31
	s_ashr_i32 s4, s4, 5
	s_add_i32 s4, s4, s6
	s_lshl_b32 s7, s4, 3
	s_mul_i32 s6, s4, 0xb0
	s_sub_i32 s4, 0x80, s7
	s_add_i32 s3, s3, s9
	s_min_i32 s8, s4, 8
	s_ashr_i32 s4, s3, 31
	s_lshr_b32 s4, s4, 27
	s_add_i32 s4, s3, s4
	s_sub_i32 s6, s5, s6
	s_ashr_i32 s5, s4, 5
	v_writelane_b32 v254, s9, 53
	s_lshl_b32 s9, s5, 3
	s_sub_i32 s5, 0x80, s9
	s_min_i32 s10, s5, 8
	s_sext_i32_i16 s5, s8
	v_cvt_f32_i32_e32 v0, s5
	v_cvt_f32_i32_e32 v1, s6
	s_andn2_b32 s4, s4, 31
	s_sub_i32 s3, s3, s4
	v_rcp_iflag_f32_e32 v2, v0
	s_xor_b32 s4, s6, s5
	s_ashr_i32 s4, s4, 30
	s_or_b32 s11, s4, 1
	v_mul_f32_e32 v2, v1, v2
	v_trunc_f32_e32 v2, v2
	v_fma_f32 v1, -v2, v0, v1
	v_cvt_i32_f32_e32 v2, v2
	v_cmp_ge_f32_e64 s[4:5], |v1|, |v0|
	s_and_b64 s[4:5], s[4:5], exec
	s_cselect_b32 s4, s11, 0
	v_readfirstlane_b32 s5, v2
	s_add_i32 s4, s5, s4
	s_sext_i32_i16 s5, s4
	s_mul_i32 s4, s4, s8
	s_sub_i32 s4, s6, s4
	s_sext_i32_i16 s4, s4
	s_add_i32 s4, s7, s4
	v_writelane_b32 v254, s4, 54
	s_lshl_b32 s4, s4, 8
	v_writelane_b32 v254, s5, 55
	s_lshl_b32 s6, s5, 8
	s_ashr_i32 s5, s4, 31
	s_lshl_b64 s[4:5], s[4:5], 11
	v_writelane_b32 v254, s4, 56
	s_ashr_i32 s7, s6, 31
	v_cvt_f32_i32_e32 v1, s3
	v_writelane_b32 v254, s5, 57
	s_lshl_b64 s[4:5], s[6:7], 11
	v_writelane_b32 v254, s4, 58
	s_nop 1
	v_writelane_b32 v254, s5, 59
	s_sext_i32_i16 s4, s10
	v_cvt_f32_i32_e32 v0, s4
	s_lshl_b32 s5, s12, 1
	s_add_u32 s6, s60, s5
	v_writelane_b32 v254, s12, 60
	v_rcp_iflag_f32_e32 v2, v0
	s_addc_u32 s7, s61, 0
	s_xor_b32 s4, s3, s4
	v_writelane_b32 v254, s6, 61
	v_mul_f32_e32 v2, v1, v2
	v_trunc_f32_e32 v2, v2
	s_ashr_i32 s4, s4, 30
	v_fma_f32 v1, -v2, v0, v1
	v_writelane_b32 v254, s7, 62
	s_or_b32 s6, s4, 1
	v_cmp_ge_f32_e64 s[4:5], |v1|, |v0|
	s_and_b64 s[4:5], s[4:5], exec
	s_load_dword s4, s[0:1], 0xb8
	v_cvt_i32_f32_e32 v0, v2
	v_mov_b32_e32 v1, 0
	s_barrier
	s_waitcnt lgkmcnt(0)
	s_mul_i32 s35, s35, s4
	s_cselect_b32 s4, s6, 0
	v_readfirstlane_b32 s5, v0
	s_add_i32 s4, s5, s4
	s_mul_i32 s5, s4, s10
	s_sub_i32 s3, s3, s5
	s_sext_i32_i16 s3, s3
	s_add_i32 s3, s9, s3
	s_lshl_b32 s6, s3, 8
	v_writelane_b32 v255, s6, 0
	s_sext_i32_i16 s4, s4
	s_ashr_i32 s95, s94, 31
	v_writelane_b32 v255, s7, 1
	v_writelane_b32 v255, s4, 2
	s_lshl_b32 s4, s4, 8
	v_writelane_b32 v255, s4, 3
	s_lshl_b64 s[86:87], s[94:95], 2
	s_lshl_b64 s[26:27], s[94:95], 1
	v_writelane_b32 v255, s5, 4
	s_add_u32 s4, s36, 0x720a000
	s_addc_u32 s5, s37, 0
	v_writelane_b32 v255, s4, 5
	v_writelane_b32 v254, s3, 63
	s_lshl_b32 s3, s34, 5
	v_writelane_b32 v255, s5, 6
	v_writelane_b32 v255, s3, 7
	s_lshl_b32 s3, s34, 7
	v_writelane_b32 v255, s3, 8
	s_add_i32 s3, 0, 0x20800
	v_writelane_b32 v255, s3, 9
	s_add_i32 s4, 0, 0x21000
	v_writelane_b32 v255, s4, 10
	s_add_i32 s4, 0, 0x21004
	v_writelane_b32 v255, s4, 11
	s_add_i32 s4, 0, 0x11000
	v_writelane_b32 v255, s4, 12
	s_add_i32 s4, 0, 0x1a400
	v_writelane_b32 v255, s4, 13
	s_add_i32 s4, 0, 0x19800
	v_writelane_b32 v255, s4, 14
	v_writelane_b32 v255, s76, 15
	s_mov_b32 s4, s94
	s_movk_i32 s95, 0xc00
	v_writelane_b32 v255, s77, 16
	v_writelane_b32 v255, s92, 17
	s_movk_i32 s3, 0x1600
	s_add_i32 s64, 0, 0x23000
	v_writelane_b32 v255, s93, 18
	v_writelane_b32 v255, s4, 19
	s_nop 1
	v_writelane_b32 v255, s5, 20
	v_writelane_b32 v255, s98, 21
	s_nop 1
	v_writelane_b32 v255, s99, 22
	v_writelane_b32 v255, s62, 23
	s_nop 1
	v_writelane_b32 v255, s63, 24
	v_writelane_b32 v255, s66, 25
	s_nop 1
	v_writelane_b32 v255, s67, 26
	v_writelane_b32 v255, s70, 27
	s_nop 1
	v_writelane_b32 v255, s71, 28
	v_writelane_b32 v255, s78, 29
	s_nop 1
	v_writelane_b32 v255, s79, 30
	v_writelane_b32 v255, s80, 31
	s_nop 1
	v_writelane_b32 v255, s81, 32
	v_writelane_b32 v255, s86, 33
	s_nop 1
	v_writelane_b32 v255, s87, 34
	v_writelane_b32 v255, s74, 35
	s_nop 1
	v_writelane_b32 v255, s75, 36
	v_writelane_b32 v255, s26, 37
	s_nop 1
	v_writelane_b32 v255, s27, 38
	s_branch .LBB0_162
